# P6 group scan: both state-row LDS read pairs of a step issued up front into private registers
# speedup vs baseline: 1.0343x; 1.0009x over previous
; #define LAS __attribute__((address_space(3)))
; __device__ __forceinline__ void rwkv_phase_b2(const Ctx& C) {
;     ...
; #pragma unroll
;             for (int s = 0; s < 4; ++s) {
;                 const int g = g0 + s; const size_t o = ob + (size_t)g * 4096;
;                 for (int e = tid; e < 1024; e += NTHR) Sg[o + (rb * 16 + (e >> 6)) * 64 + (e & 63)] = MAT(0)[(e >> 6) * MS + (e & 63)];
;                 f32x4 a0 = (f32x4){0.f, 0.f, 0.f, 0.f}, a1 = a0; float qc[4];
;                 if (w < 4) {
;                     const LAS float* m0 = MAT(0);
; #pragma unroll
;                     for (int kb = 0; kb < 4; kb += 2) {
;                         const f32x4 s0 = *(const LAS f32x4*)(m0 + l15 * MS + 16 * kb + 4 * q), s1 = *(const LAS f32x4*)(m0 + l15 * MS + 16 * (kb + 1) + 4 * q);
; #pragma unroll
;                         for (int j = 0; j < 4; ++j) {
;                             a0 = __builtin_amdgcn_mfma_f32_16x16x4f32(s0[j], pv[s][4 * kb + j], a0, 0, 0, 0);
;                             a1 = __builtin_amdgcn_mfma_f32_16x16x4f32(s1[j], pv[s][4 * (kb + 1) + j], a1, 0, 0, 0);
;                         }
;                     }
; #pragma unroll
;                     for (int j = 0; j < 4; ++j) qc[j] = qv[s][j];
;                     if (g + 4 < NGRP) {
; #pragma unroll
;                         for (int i = 0; i < 16; ++i) pv[s][i] = Pc[o + 4 * 4096 + poff + ((i & 3) + 16 * (i >> 2)) * 64];
; #pragma unroll
;                         for (int j = 0; j < 4; ++j) qv[s][j] = Qc[o + 4 * 4096 + qoff + j * 64];
;                     }
.LBB0_968:
	s_lshl_b32 s36, s35, 12
	v_mov_b32_e32 v2, 0
	s_and_b64 vcc, exec, s[16:17]
	s_cbranch_vccz .LBB0_973
	ds_read_b128 v[2:5], v35
	ds_read_b128 v[6:9], v35 offset:64
	ds_read_b128 v[164:167], v35 offset:128
	ds_read_b128 v[168:171], v35 offset:192
	s_cmp_gt_u32 s35, 27
	v_mov_b32_e32 v105, v119
	s_waitcnt lgkmcnt(3)
	v_mfma_f32_16x16x4_f32 v[106:109], v2, v48, 0
	s_waitcnt lgkmcnt(2)
	v_mfma_f32_16x16x4_f32 v[134:137], v6, v49, 0
	v_mfma_f32_16x16x4_f32 v[106:109], v3, v41, v[106:109]
	v_mfma_f32_16x16x4_f32 v[134:137], v7, v50, v[134:137]
	v_mfma_f32_16x16x4_f32 v[106:109], v4, v42, v[106:109]
	v_mfma_f32_16x16x4_f32 v[134:137], v8, v51, v[134:137]
	v_mfma_f32_16x16x4_f32 v[2:5], v5, v43, v[106:109]
	v_mfma_f32_16x16x4_f32 v[6:9], v9, v53, v[134:137]
	s_waitcnt lgkmcnt(1)
	v_mfma_f32_16x16x4_f32 v[2:5], v164, v57, v[2:5]
	v_mov_b32_e32 v106, v118
	s_waitcnt lgkmcnt(0)
	v_mfma_f32_16x16x4_f32 v[6:9], v168, v44, v[6:9]
	v_mfma_f32_16x16x4_f32 v[2:5], v165, v52, v[2:5]
	v_mov_b32_e32 v107, v120
	v_mfma_f32_16x16x4_f32 v[6:9], v169, v45, v[6:9]
	v_mfma_f32_16x16x4_f32 v[2:5], v166, v54, v[2:5]
	v_mov_b32_e32 v108, v117
	v_mfma_f32_16x16x4_f32 v[6:9], v170, v46, v[6:9]
	v_mfma_f32_16x16x4_f32 v[2:5], v167, v55, v[2:5]
	v_mfma_f32_16x16x4_f32 v[6:9], v171, v47, v[6:9]
	s_cbranch_scc1 .LBB0_974
	s_add_u32 s38, s22, s36
	s_addc_u32 s39, s23, 0
	s_lshl_b64 s[38:39], s[38:39], 2
	s_add_u32 s42, s10, s38
	s_addc_u32 s43, s11, s39
	v_lshl_add_u64 v[42:43], v[10:11], 2, s[42:43]
	v_add_co_u32_e32 v108, vcc, s30, v42
	s_add_u32 s38, s12, s38
	s_nop 0
	v_addc_co_u32_e32 v109, vcc, 0, v43, vcc
	v_add_co_u32_e32 v50, vcc, s31, v42
	s_addc_u32 s39, s13, s39
	s_nop 0
	v_addc_co_u32_e32 v51, vcc, 0, v43, vcc
	v_add_co_u32_e32 v110, vcc, s33, v42
	v_lshl_add_u64 v[48:49], v[42:43], 0, s[20:21]
	s_nop 0
	v_addc_co_u32_e32 v111, vcc, 0, v43, vcc
	v_lshl_add_u64 v[42:43], v[12:13], 2, s[38:39]
	v_add_co_u32_e32 v134, vcc, 0x10000, v42
	global_load_dword v44, v[110:111], off
	global_load_dword v45, v[110:111], off offset:256
	global_load_dword v46, v[110:111], off offset:512
	global_load_dword v47, v[110:111], off offset:768
	v_lshl_add_u64 v[126:127], v[42:43], 0, s[20:21]
	v_addc_co_u32_e32 v135, vcc, 0, v43, vcc
	global_load_dword v41, v[48:49], off offset:256
	global_load_dword v42, v[48:49], off offset:512
	global_load_dword v43, v[48:49], off offset:768
	global_load_dword v52, v[50:51], off offset:256
	global_load_dword v54, v[50:51], off offset:512
	global_load_dword v55, v[50:51], off offset:768
	global_load_dword v105, v[126:127], off offset:256
	global_load_dword v106, v[126:127], off offset:512
	global_load_dword v48, v[108:109], off offset:-4096
	global_load_dword v49, v[108:109], off
	s_nop 0
	global_load_dword v50, v[108:109], off offset:256
	global_load_dword v51, v[108:109], off offset:512
	global_load_dword v53, v[108:109], off offset:768
	global_load_dword v57, v[110:111], off offset:-4096
	global_load_dword v107, v[134:135], off
	s_nop 0
	global_load_dword v108, v[126:127], off offset:768
	s_branch .LBB0_974

; #define LAS __attribute__((address_space(3)))
; __device__ __forceinline__ void rwkv_phase_b2(const Ctx& C) {
;     ...
; #pragma unroll
;             for (int s = 0; s < 4; ++s) {
;                 const int g = g0 + s; const size_t o = ob + (size_t)g * 4096;
;                 for (int e = tid; e < 1024; e += NTHR) Sg[o + (rb * 16 + (e >> 6)) * 64 + (e & 63)] = MAT(0)[(e >> 6) * MS + (e & 63)];
;                 f32x4 a0 = (f32x4){0.f, 0.f, 0.f, 0.f}, a1 = a0; float qc[4];
;                 if (w < 4) {
;                     const LAS float* m0 = MAT(0);
; #pragma unroll
;                     for (int kb = 0; kb < 4; kb += 2) {
;                         const f32x4 s0 = *(const LAS f32x4*)(m0 + l15 * MS + 16 * kb + 4 * q), s1 = *(const LAS f32x4*)(m0 + l15 * MS + 16 * (kb + 1) + 4 * q);
; #pragma unroll
;                         for (int j = 0; j < 4; ++j) {
;                             a0 = __builtin_amdgcn_mfma_f32_16x16x4f32(s0[j], pv[s][4 * kb + j], a0, 0, 0, 0);
;                             a1 = __builtin_amdgcn_mfma_f32_16x16x4f32(s1[j], pv[s][4 * (kb + 1) + j], a1, 0, 0, 0);
;                         }
;                     }
; #pragma unroll
;                     for (int j = 0; j < 4; ++j) qc[j] = qv[s][j];
;                     if (g + 4 < NGRP) {
; #pragma unroll
;                         for (int i = 0; i < 16; ++i) pv[s][i] = Pc[o + 4 * 4096 + poff + ((i & 3) + 16 * (i >> 2)) * 64];
; #pragma unroll
;                         for (int j = 0; j < 4; ++j) qv[s][j] = Qc[o + 4 * 4096 + qoff + j * 64];
;                     }
.LBB0_976:
	s_nop 3
	s_waitcnt lgkmcnt(0)
	s_barrier
	s_and_b64 vcc, exec, s[6:7]
	v_mov_b32_e32 v2, 0
	s_cbranch_vccnz .LBB0_981
	ds_read_b128 v[2:5], v35
	ds_read_b128 v[6:9], v35 offset:64
	ds_read_b128 v[164:167], v35 offset:128
	ds_read_b128 v[168:171], v35 offset:192
	s_cmp_gt_u32 s35, 27
	v_mov_b32_e32 v109, v132
	v_mov_b32_e32 v110, v131
	s_waitcnt lgkmcnt(3)
	v_mfma_f32_16x16x4_f32 v[134:137], v2, v64, 0
	v_mov_b32_e32 v111, v130
	v_mov_b32_e32 v112, v129
	s_waitcnt lgkmcnt(2)
	v_mfma_f32_16x16x4_f32 v[138:141], v6, v103, 0
	v_mfma_f32_16x16x4_f32 v[134:137], v3, v56, v[134:137]
	v_mfma_f32_16x16x4_f32 v[138:141], v7, v65, v[138:141]
	v_mfma_f32_16x16x4_f32 v[134:137], v4, v58, v[134:137]
	v_mfma_f32_16x16x4_f32 v[138:141], v8, v66, v[138:141]
	v_mfma_f32_16x16x4_f32 v[2:5], v5, v59, v[134:137]
	v_mfma_f32_16x16x4_f32 v[6:9], v9, v67, v[138:141]
	s_waitcnt lgkmcnt(1)
	v_mfma_f32_16x16x4_f32 v[2:5], v164, v104, v[2:5]
	s_waitcnt lgkmcnt(0)
	v_mfma_f32_16x16x4_f32 v[6:9], v168, v60, v[6:9]
	v_mfma_f32_16x16x4_f32 v[2:5], v165, v98, v[2:5]
	v_mfma_f32_16x16x4_f32 v[6:9], v169, v61, v[6:9]
	v_mfma_f32_16x16x4_f32 v[2:5], v166, v100, v[2:5]
	v_mfma_f32_16x16x4_f32 v[6:9], v170, v62, v[6:9]
	v_mfma_f32_16x16x4_f32 v[2:5], v167, v102, v[2:5]
	v_mfma_f32_16x16x4_f32 v[6:9], v171, v63, v[6:9]
	s_cbranch_scc1 .LBB0_982
	s_or_b32 s37, s36, 0x1000
	s_add_u32 s38, s22, s37
	s_addc_u32 s39, s23, 0
	s_lshl_b64 s[38:39], s[38:39], 2
	s_add_u32 s42, s10, s38
	s_addc_u32 s43, s11, s39
	v_lshl_add_u64 v[58:59], v[10:11], 2, s[42:43]
	v_add_co_u32_e32 v118, vcc, s30, v58
	s_add_u32 s38, s12, s38
	s_nop 0
	v_addc_co_u32_e32 v119, vcc, 0, v59, vcc
	v_add_co_u32_e32 v66, vcc, s31, v58
	s_addc_u32 s39, s13, s39
	s_nop 0
	v_addc_co_u32_e32 v67, vcc, 0, v59, vcc
	v_add_co_u32_e32 v126, vcc, s33, v58
	v_lshl_add_u64 v[64:65], v[58:59], 0, s[20:21]
	s_nop 0
	v_addc_co_u32_e32 v127, vcc, 0, v59, vcc
	v_lshl_add_u64 v[58:59], v[12:13], 2, s[38:39]
	v_add_co_u32_e32 v136, vcc, 0x10000, v58
	global_load_dword v60, v[126:127], off
	global_load_dword v61, v[126:127], off offset:256
	global_load_dword v62, v[126:127], off offset:512
	global_load_dword v63, v[126:127], off offset:768
	v_lshl_add_u64 v[134:135], v[58:59], 0, s[20:21]
	v_addc_co_u32_e32 v137, vcc, 0, v59, vcc
	global_load_dword v56, v[64:65], off offset:256
	global_load_dword v58, v[64:65], off offset:512
	global_load_dword v59, v[64:65], off offset:768
	global_load_dword v98, v[66:67], off offset:256
	global_load_dword v100, v[66:67], off offset:512
	global_load_dword v102, v[66:67], off offset:768
	global_load_dword v110, v[134:135], off offset:256
	global_load_dword v111, v[134:135], off offset:512
	global_load_dword v64, v[118:119], off offset:-4096
	global_load_dword v103, v[118:119], off
	global_load_dword v65, v[118:119], off offset:256
	global_load_dword v66, v[118:119], off offset:512
	global_load_dword v67, v[118:119], off offset:768
	global_load_dword v104, v[126:127], off offset:-4096
	global_load_dword v109, v[136:137], off
	global_load_dword v112, v[134:135], off offset:768
	s_branch .LBB0_982

; #define LAS __attribute__((address_space(3)))
; __device__ __forceinline__ void rwkv_phase_b2(const Ctx& C) {
;     ...
; #pragma unroll
;             for (int s = 0; s < 4; ++s) {
;                 const int g = g0 + s; const size_t o = ob + (size_t)g * 4096;
;                 for (int e = tid; e < 1024; e += NTHR) Sg[o + (rb * 16 + (e >> 6)) * 64 + (e & 63)] = MAT(0)[(e >> 6) * MS + (e & 63)];
;                 f32x4 a0 = (f32x4){0.f, 0.f, 0.f, 0.f}, a1 = a0; float qc[4];
;                 if (w < 4) {
;                     const LAS float* m0 = MAT(0);
; #pragma unroll
;                     for (int kb = 0; kb < 4; kb += 2) {
;                         const f32x4 s0 = *(const LAS f32x4*)(m0 + l15 * MS + 16 * kb + 4 * q), s1 = *(const LAS f32x4*)(m0 + l15 * MS + 16 * (kb + 1) + 4 * q);
; #pragma unroll
;                         for (int j = 0; j < 4; ++j) {
;                             a0 = __builtin_amdgcn_mfma_f32_16x16x4f32(s0[j], pv[s][4 * kb + j], a0, 0, 0, 0);
;                             a1 = __builtin_amdgcn_mfma_f32_16x16x4f32(s1[j], pv[s][4 * (kb + 1) + j], a1, 0, 0, 0);
;                         }
;                     }
; #pragma unroll
;                     for (int j = 0; j < 4; ++j) qc[j] = qv[s][j];
;                     if (g + 4 < NGRP) {
; #pragma unroll
;                         for (int i = 0; i < 16; ++i) pv[s][i] = Pc[o + 4 * 4096 + poff + ((i & 3) + 16 * (i >> 2)) * 64];
; #pragma unroll
;                         for (int j = 0; j < 4; ++j) qv[s][j] = Qc[o + 4 * 4096 + qoff + j * 64];
;                     }
.LBB0_984:
	s_nop 3
	s_waitcnt lgkmcnt(0)
	s_barrier
	s_and_b64 vcc, exec, s[6:7]
	v_mov_b32_e32 v2, 0
	s_cbranch_vccnz .LBB0_989
	ds_read_b128 v[2:5], v35
	ds_read_b128 v[6:9], v35 offset:64
	ds_read_b128 v[164:167], v35 offset:128
	ds_read_b128 v[168:171], v35 offset:192
	s_cmp_gt_u32 s35, 27
	v_mov_b32_e32 v118, v124
	v_mov_b32_e32 v117, v123
	s_waitcnt lgkmcnt(3)
	v_mfma_f32_16x16x4_f32 v[126:129], v2, v75, 0
	v_mov_b32_e32 v119, v122
	v_mov_b32_e32 v120, v121
	s_waitcnt lgkmcnt(2)
	v_mfma_f32_16x16x4_f32 v[130:133], v6, v99, 0
	v_mfma_f32_16x16x4_f32 v[126:129], v3, v69, v[126:129]
	v_mfma_f32_16x16x4_f32 v[130:133], v7, v76, v[130:133]
	v_mfma_f32_16x16x4_f32 v[126:129], v4, v71, v[126:129]
	v_mfma_f32_16x16x4_f32 v[130:133], v8, v77, v[130:133]
	v_mfma_f32_16x16x4_f32 v[2:5], v5, v73, v[126:129]
	v_mfma_f32_16x16x4_f32 v[6:9], v9, v78, v[130:133]
	s_waitcnt lgkmcnt(1)
	v_mfma_f32_16x16x4_f32 v[2:5], v164, v101, v[2:5]
	s_waitcnt lgkmcnt(0)
	v_mfma_f32_16x16x4_f32 v[6:9], v168, v68, v[6:9]
	v_mfma_f32_16x16x4_f32 v[2:5], v165, v92, v[2:5]
	v_mfma_f32_16x16x4_f32 v[6:9], v169, v70, v[6:9]
	v_mfma_f32_16x16x4_f32 v[2:5], v166, v94, v[2:5]
	v_mfma_f32_16x16x4_f32 v[6:9], v170, v72, v[6:9]
	v_mfma_f32_16x16x4_f32 v[2:5], v167, v95, v[2:5]
	v_mfma_f32_16x16x4_f32 v[6:9], v171, v74, v[6:9]
	s_cbranch_scc1 .LBB0_990
	s_or_b32 s37, s36, 0x2000
	s_add_u32 s38, s22, s37
	s_addc_u32 s39, s23, 0
	s_lshl_b64 s[38:39], s[38:39], 2
	s_add_u32 s42, s10, s38
	s_addc_u32 s43, s11, s39
	v_lshl_add_u64 v[68:69], v[10:11], 2, s[42:43]
	v_add_co_u32_e32 v126, vcc, s30, v68
	s_add_u32 s38, s12, s38
	s_nop 0
	v_addc_co_u32_e32 v127, vcc, 0, v69, vcc
	v_add_co_u32_e32 v118, vcc, s31, v68
	s_addc_u32 s39, s13, s39
	s_nop 0
	v_addc_co_u32_e32 v119, vcc, 0, v69, vcc
	v_add_co_u32_e32 v128, vcc, s33, v68
	v_lshl_add_u64 v[94:95], v[12:13], 2, s[38:39]
	s_nop 0
	v_addc_co_u32_e32 v129, vcc, 0, v69, vcc
	v_lshl_add_u64 v[76:77], v[68:69], 0, s[20:21]
	v_add_co_u32_e32 v132, vcc, 0x10000, v94
	global_load_dword v68, v[128:129], off
	global_load_dword v70, v[128:129], off offset:256
	global_load_dword v72, v[128:129], off offset:512
	global_load_dword v74, v[128:129], off offset:768
	v_lshl_add_u64 v[130:131], v[94:95], 0, s[20:21]
	v_addc_co_u32_e32 v133, vcc, 0, v95, vcc
	global_load_dword v69, v[76:77], off offset:256
	global_load_dword v71, v[76:77], off offset:512
	global_load_dword v73, v[76:77], off offset:768
	global_load_dword v92, v[118:119], off offset:256
	global_load_dword v94, v[118:119], off offset:512
	global_load_dword v95, v[118:119], off offset:768
	global_load_dword v117, v[130:131], off offset:256
	s_nop 0
	global_load_dword v119, v[130:131], off offset:512
	global_load_dword v75, v[126:127], off offset:-4096
	global_load_dword v99, v[126:127], off
	global_load_dword v76, v[126:127], off offset:256
	global_load_dword v77, v[126:127], off offset:512
	global_load_dword v78, v[126:127], off offset:768
	global_load_dword v101, v[128:129], off offset:-4096
	global_load_dword v118, v[132:133], off
	global_load_dword v120, v[130:131], off offset:768
	s_branch .LBB0_990

; #define LAS __attribute__((address_space(3)))
; __device__ __forceinline__ void rwkv_phase_b2(const Ctx& C) {
;     ...
; #pragma unroll
;             for (int s = 0; s < 4; ++s) {
;                 const int g = g0 + s; const size_t o = ob + (size_t)g * 4096;
;                 for (int e = tid; e < 1024; e += NTHR) Sg[o + (rb * 16 + (e >> 6)) * 64 + (e & 63)] = MAT(0)[(e >> 6) * MS + (e & 63)];
;                 f32x4 a0 = (f32x4){0.f, 0.f, 0.f, 0.f}, a1 = a0; float qc[4];
;                 if (w < 4) {
;                     const LAS float* m0 = MAT(0);
; #pragma unroll
;                     for (int kb = 0; kb < 4; kb += 2) {
;                         const f32x4 s0 = *(const LAS f32x4*)(m0 + l15 * MS + 16 * kb + 4 * q), s1 = *(const LAS f32x4*)(m0 + l15 * MS + 16 * (kb + 1) + 4 * q);
; #pragma unroll
;                         for (int j = 0; j < 4; ++j) {
;                             a0 = __builtin_amdgcn_mfma_f32_16x16x4f32(s0[j], pv[s][4 * kb + j], a0, 0, 0, 0);
;                             a1 = __builtin_amdgcn_mfma_f32_16x16x4f32(s1[j], pv[s][4 * (kb + 1) + j], a1, 0, 0, 0);
;                         }
;                     }
; #pragma unroll
;                     for (int j = 0; j < 4; ++j) qc[j] = qv[s][j];
;                     if (g + 4 < NGRP) {
; #pragma unroll
;                         for (int i = 0; i < 16; ++i) pv[s][i] = Pc[o + 4 * 4096 + poff + ((i & 3) + 16 * (i >> 2)) * 64];
; #pragma unroll
;                         for (int j = 0; j < 4; ++j) qv[s][j] = Qc[o + 4 * 4096 + qoff + j * 64];
;                     }
.LBB0_992:
	s_nop 3
	s_waitcnt lgkmcnt(0)
	s_barrier
	s_and_b64 vcc, exec, s[6:7]
	v_mov_b32_e32 v2, 0
	s_cbranch_vccnz .LBB0_998
	s_waitcnt vmcnt(16)
	v_mov_b32_e32 v113, v163
	v_mov_b32_e32 v114, v161
	v_mov_b32_e32 v115, v160
	v_mov_b32_e32 v116, v162
	ds_read_b128 v[2:5], v35
	ds_read_b128 v[6:9], v35 offset:64
	ds_read_b128 v[164:167], v35 offset:128
	ds_read_b128 v[168:171], v35 offset:192
	s_cmp_gt_u32 s35, 27
	s_waitcnt lgkmcnt(3)
	v_mfma_f32_16x16x4_f32 v[122:125], v2, v89, 0
	s_waitcnt lgkmcnt(2)
	v_mfma_f32_16x16x4_f32 v[126:129], v6, v93, 0
	v_mfma_f32_16x16x4_f32 v[122:125], v3, v79, v[122:125]
	v_mfma_f32_16x16x4_f32 v[126:129], v7, v90, v[126:129]
	v_mfma_f32_16x16x4_f32 v[122:125], v4, v80, v[122:125]
	v_mfma_f32_16x16x4_f32 v[126:129], v8, v91, v[126:129]
	v_mfma_f32_16x16x4_f32 v[2:5], v5, v81, v[122:125]
	v_mfma_f32_16x16x4_f32 v[6:9], v9, v97, v[126:129]
	v_mov_b32_e32 v129, v115
	s_waitcnt lgkmcnt(1)
	v_mfma_f32_16x16x4_f32 v[2:5], v164, v96, v[2:5]
	s_waitcnt lgkmcnt(0)
	v_mfma_f32_16x16x4_f32 v[6:9], v168, v82, v[6:9]
	v_mov_b32_e32 v130, v114
	v_mfma_f32_16x16x4_f32 v[2:5], v165, v86, v[2:5]
	v_mfma_f32_16x16x4_f32 v[6:9], v169, v83, v[6:9]
	v_mov_b32_e32 v131, v116
	v_mfma_f32_16x16x4_f32 v[2:5], v166, v87, v[2:5]
	v_mfma_f32_16x16x4_f32 v[6:9], v170, v84, v[6:9]
	v_mov_b32_e32 v132, v113
	v_mfma_f32_16x16x4_f32 v[2:5], v167, v88, v[2:5]
	v_mfma_f32_16x16x4_f32 v[6:9], v171, v85, v[6:9]
	s_cbranch_scc1 .LBB0_997
	s_or_b32 s36, s36, 0x3000
	s_add_u32 s36, s22, s36
	s_addc_u32 s37, s23, 0
	s_lshl_b64 s[36:37], s[36:37], 2
	s_add_u32 s38, s10, s36
	s_addc_u32 s39, s11, s37
	v_lshl_add_u64 v[80:81], v[10:11], 2, s[38:39]
	v_add_co_u32_e32 v96, vcc, s30, v80
	s_add_u32 s36, s12, s36
	s_nop 0
	v_addc_co_u32_e32 v97, vcc, 0, v81, vcc
	v_add_co_u32_e32 v88, vcc, s31, v80
	s_addc_u32 s37, s13, s37
	s_nop 0
	v_addc_co_u32_e32 v89, vcc, 0, v81, vcc
	v_add_co_u32_e32 v122, vcc, s33, v80
	v_lshl_add_u64 v[86:87], v[80:81], 0, s[20:21]
	s_nop 0
	v_addc_co_u32_e32 v123, vcc, 0, v81, vcc
	v_lshl_add_u64 v[80:81], v[12:13], 2, s[36:37]
	v_add_co_u32_e32 v126, vcc, 0x10000, v80
	global_load_dword v82, v[122:123], off
	global_load_dword v83, v[122:123], off offset:256
	global_load_dword v84, v[122:123], off offset:512
	global_load_dword v85, v[122:123], off offset:768
	v_lshl_add_u64 v[124:125], v[80:81], 0, s[20:21]
	v_addc_co_u32_e32 v127, vcc, 0, v81, vcc
	global_load_dword v79, v[86:87], off offset:256
	global_load_dword v80, v[86:87], off offset:512
	global_load_dword v81, v[86:87], off offset:768
	s_nop 0
	global_load_dword v86, v[88:89], off offset:256
	global_load_dword v87, v[88:89], off offset:512
	s_nop 0
	global_load_dword v88, v[88:89], off offset:768
	s_nop 0
	global_load_dword v160, v[124:125], off offset:256
	global_load_dword v161, v[124:125], off offset:512
	global_load_dword v89, v[96:97], off offset:-4096
	global_load_dword v93, v[96:97], off
	global_load_dword v90, v[96:97], off offset:256
	global_load_dword v91, v[96:97], off offset:512
	s_nop 0
	global_load_dword v97, v[96:97], off offset:768
	s_nop 0
	global_load_dword v96, v[122:123], off offset:-4096
	global_load_dword v162, v[126:127], off
	global_load_dword v163, v[124:125], off offset:768
